# PE merge-gate epilogue: gate loads all in flight with counted waits instead of 16 serialized load-wait-store steps
# speedup vs baseline: 1.0019x; 1.0019x over previous
.LBB0_131:
	v_lshl_add_u32 v140, s23, 8, v142
	v_lshl_or_b32 v138, s22, 8, v144
	v_readlane_b32 s10, v251, 45
	v_readlane_b32 s11, v251, 46
	v_readlane_b32 s8, v253, 23
	v_readlane_b32 s9, v253, 24
	v_ashrrev_i32_e32 v139, 31, v138
	v_lshlrev_b64 v[138:139], 1, v[138:139]
	v_mov_b32_e32 v146, v140
	v_ashrrev_i32_e32 v147, 31, v146
	v_lshlrev_b64 v[146:147], 12, v[146:147]
	v_lshl_add_u64 v[146:147], s[10:11], 0, v[146:147]
	v_lshl_add_u64 v[146:147], v[146:147], 0, v[138:139]
	global_load_dwordx4 v[204:207], v[146:147], off
	global_load_dwordx4 v[208:211], v[146:147], off offset:256
	v_add_u32_e32 v146, 0x10, v140
	v_ashrrev_i32_e32 v147, 31, v146
	v_lshlrev_b64 v[146:147], 12, v[146:147]
	v_lshl_add_u64 v[146:147], s[10:11], 0, v[146:147]
	v_lshl_add_u64 v[146:147], v[146:147], 0, v[138:139]
	global_load_dwordx4 v[212:215], v[146:147], off
	global_load_dwordx4 v[216:219], v[146:147], off offset:256
	v_add_u32_e32 v146, 0x20, v140
	v_ashrrev_i32_e32 v147, 31, v146
	v_lshlrev_b64 v[146:147], 12, v[146:147]
	v_lshl_add_u64 v[146:147], s[10:11], 0, v[146:147]
	v_lshl_add_u64 v[146:147], v[146:147], 0, v[138:139]
	global_load_dwordx4 v[220:223], v[146:147], off
	global_load_dwordx4 v[224:227], v[146:147], off offset:256
	v_add_u32_e32 v146, 0x30, v140
	v_ashrrev_i32_e32 v147, 31, v146
	v_lshlrev_b64 v[146:147], 12, v[146:147]
	v_lshl_add_u64 v[146:147], s[10:11], 0, v[146:147]
	v_lshl_add_u64 v[146:147], v[146:147], 0, v[138:139]
	global_load_dwordx4 v[228:231], v[146:147], off
	global_load_dwordx4 v[232:235], v[146:147], off offset:256
	v_add_u32_e32 v146, 0x80, v140
	v_ashrrev_i32_e32 v147, 31, v146
	v_lshlrev_b64 v[146:147], 12, v[146:147]
	v_lshl_add_u64 v[146:147], s[10:11], 0, v[146:147]
	v_lshl_add_u64 v[146:147], v[146:147], 0, v[138:139]
	global_load_dwordx4 v[236:239], v[146:147], off
	global_load_dwordx4 v[240:243], v[146:147], off offset:256
	v_add_u32_e32 v146, 0x90, v140
	v_ashrrev_i32_e32 v147, 31, v146
	v_lshlrev_b64 v[146:147], 12, v[146:147]
	v_lshl_add_u64 v[146:147], s[10:11], 0, v[146:147]
	v_lshl_add_u64 v[146:147], v[146:147], 0, v[138:139]
	global_load_dwordx4 v[168:171], v[146:147], off
	global_load_dwordx4 v[172:175], v[146:147], off offset:256
	v_add_u32_e32 v150, 0xa0, v140
	v_ashrrev_i32_e32 v151, 31, v150
	v_lshlrev_b64 v[150:151], 12, v[150:151]
	v_lshl_add_u64 v[150:151], s[10:11], 0, v[150:151]
	v_lshl_add_u64 v[150:151], v[150:151], 0, v[138:139]
	global_load_dwordx4 v[176:179], v[150:151], off
	v_add_u32_e32 v152, 0xb0, v140
	v_ashrrev_i32_e32 v153, 31, v152
	v_lshlrev_b64 v[152:153], 12, v[152:153]
	v_lshl_add_u64 v[152:153], s[10:11], 0, v[152:153]
	v_lshl_add_u64 v[152:153], v[152:153], 0, v[138:139]
	s_waitcnt vmcnt(12)
	v_lshlrev_b32_e32 v154, 16, v204
	v_and_b32_e32 v155, 0xffff0000, v204
	v_mul_f32_e32 v124, v124, v154
	v_mul_f32_e32 v125, v125, v155
	v_lshlrev_b32_e32 v158, 16, v205
	v_and_b32_e32 v141, 0xffff0000, v205
	v_mul_f32_e32 v126, v126, v158
	v_mul_f32_e32 v127, v127, v141
	v_lshlrev_b32_e32 v154, 16, v206
	v_and_b32_e32 v155, 0xffff0000, v206
	v_mul_f32_e32 v120, v120, v154
	v_mul_f32_e32 v121, v121, v155
	v_lshlrev_b32_e32 v158, 16, v207
	v_and_b32_e32 v141, 0xffff0000, v207
	v_mul_f32_e32 v122, v122, v158
	v_mul_f32_e32 v123, v123, v141
	v_mov_b32_e32 v148, v140
	v_ashrrev_i32_e32 v149, 31, v148
	v_lshlrev_b64 v[148:149], 11, v[148:149]
	v_lshl_add_u64 v[148:149], s[8:9], 0, v[148:149]
	v_lshl_add_u64 v[148:149], v[148:149], 0, v[138:139]
	v_cvt_pk_bf16_f32 v124, v124, v125
	v_cvt_pk_bf16_f32 v125, v126, v127
	v_cvt_pk_bf16_f32 v126, v120, v121
	v_cvt_pk_bf16_f32 v127, v122, v123
	global_store_dwordx4 v[148:149], v[124:127], off
	global_load_dwordx4 v[204:207], v[150:151], off offset:256
	s_waitcnt vmcnt(13)
	v_lshlrev_b32_e32 v154, 16, v208
	v_and_b32_e32 v155, 0xffff0000, v208
	v_mul_f32_e32 v116, v116, v154
	v_mul_f32_e32 v117, v117, v155
	v_lshlrev_b32_e32 v158, 16, v209
	v_and_b32_e32 v141, 0xffff0000, v209
	v_mul_f32_e32 v118, v118, v158
	v_mul_f32_e32 v119, v119, v141
	v_lshlrev_b32_e32 v154, 16, v210
	v_and_b32_e32 v155, 0xffff0000, v210
	v_mul_f32_e32 v112, v112, v154
	v_mul_f32_e32 v113, v113, v155
	v_lshlrev_b32_e32 v158, 16, v211
	v_and_b32_e32 v141, 0xffff0000, v211
	v_mul_f32_e32 v114, v114, v158
	v_mul_f32_e32 v115, v115, v141
	v_cvt_pk_bf16_f32 v116, v116, v117
	v_cvt_pk_bf16_f32 v117, v118, v119
	v_cvt_pk_bf16_f32 v118, v112, v113
	v_cvt_pk_bf16_f32 v119, v114, v115
	global_store_dwordx4 v[148:149], v[116:119], off offset:256
	global_load_dwordx4 v[208:211], v[152:153], off
	s_waitcnt vmcnt(14)
	v_lshlrev_b32_e32 v154, 16, v212
	v_and_b32_e32 v155, 0xffff0000, v212
	v_mul_f32_e32 v108, v108, v154
	v_mul_f32_e32 v109, v109, v155
	v_lshlrev_b32_e32 v158, 16, v213
	v_and_b32_e32 v141, 0xffff0000, v213
	v_mul_f32_e32 v110, v110, v158
	v_mul_f32_e32 v111, v111, v141
	v_lshlrev_b32_e32 v154, 16, v214
	v_and_b32_e32 v155, 0xffff0000, v214
	v_mul_f32_e32 v104, v104, v154
	v_mul_f32_e32 v105, v105, v155
	v_lshlrev_b32_e32 v158, 16, v215
	v_and_b32_e32 v141, 0xffff0000, v215
	v_mul_f32_e32 v106, v106, v158
	v_mul_f32_e32 v107, v107, v141
	v_add_u32_e32 v148, 0x10, v140
	v_ashrrev_i32_e32 v149, 31, v148
	v_lshlrev_b64 v[148:149], 11, v[148:149]
	v_lshl_add_u64 v[148:149], s[8:9], 0, v[148:149]
	v_lshl_add_u64 v[148:149], v[148:149], 0, v[138:139]
	v_cvt_pk_bf16_f32 v108, v108, v109
	v_cvt_pk_bf16_f32 v109, v110, v111
	v_cvt_pk_bf16_f32 v110, v104, v105
	v_cvt_pk_bf16_f32 v111, v106, v107
	global_store_dwordx4 v[148:149], v[108:111], off
	global_load_dwordx4 v[212:215], v[152:153], off offset:256
	s_waitcnt vmcnt(15)
	v_lshlrev_b32_e32 v154, 16, v216
	v_and_b32_e32 v155, 0xffff0000, v216
	v_mul_f32_e32 v100, v100, v154
	v_mul_f32_e32 v101, v101, v155
	v_lshlrev_b32_e32 v158, 16, v217
	v_and_b32_e32 v141, 0xffff0000, v217
	v_mul_f32_e32 v102, v102, v158
	v_mul_f32_e32 v103, v103, v141
	v_lshlrev_b32_e32 v154, 16, v218
	v_and_b32_e32 v155, 0xffff0000, v218
	v_mul_f32_e32 v96, v96, v154
	v_mul_f32_e32 v97, v97, v155
	v_lshlrev_b32_e32 v158, 16, v219
	v_and_b32_e32 v141, 0xffff0000, v219
	v_mul_f32_e32 v98, v98, v158
	v_mul_f32_e32 v99, v99, v141
	v_cvt_pk_bf16_f32 v100, v100, v101
	v_cvt_pk_bf16_f32 v101, v102, v103
	v_cvt_pk_bf16_f32 v102, v96, v97
	v_cvt_pk_bf16_f32 v103, v98, v99
	global_store_dwordx4 v[148:149], v[100:103], off offset:256
	s_waitcnt vmcnt(15)
	v_lshlrev_b32_e32 v154, 16, v220
	v_and_b32_e32 v155, 0xffff0000, v220
	v_mul_f32_e32 v92, v92, v154
	v_mul_f32_e32 v93, v93, v155
	v_lshlrev_b32_e32 v158, 16, v221
	v_and_b32_e32 v141, 0xffff0000, v221
	v_mul_f32_e32 v94, v94, v158
	v_mul_f32_e32 v95, v95, v141
	v_lshlrev_b32_e32 v154, 16, v222
	v_and_b32_e32 v155, 0xffff0000, v222
	v_mul_f32_e32 v88, v88, v154
	v_mul_f32_e32 v89, v89, v155
	v_lshlrev_b32_e32 v158, 16, v223
	v_and_b32_e32 v141, 0xffff0000, v223
	v_mul_f32_e32 v90, v90, v158
	v_mul_f32_e32 v91, v91, v141
	v_add_u32_e32 v148, 0x20, v140
	v_ashrrev_i32_e32 v149, 31, v148
	v_lshlrev_b64 v[148:149], 11, v[148:149]
	v_lshl_add_u64 v[148:149], s[8:9], 0, v[148:149]
	v_lshl_add_u64 v[148:149], v[148:149], 0, v[138:139]
	v_cvt_pk_bf16_f32 v92, v92, v93
	v_cvt_pk_bf16_f32 v93, v94, v95
	v_cvt_pk_bf16_f32 v94, v88, v89
	v_cvt_pk_bf16_f32 v95, v90, v91
	global_store_dwordx4 v[148:149], v[92:95], off
	s_waitcnt vmcnt(15)
	v_lshlrev_b32_e32 v154, 16, v224
	v_and_b32_e32 v155, 0xffff0000, v224
	v_mul_f32_e32 v84, v84, v154
	v_mul_f32_e32 v85, v85, v155
	v_lshlrev_b32_e32 v158, 16, v225
	v_and_b32_e32 v141, 0xffff0000, v225
	v_mul_f32_e32 v86, v86, v158
	v_mul_f32_e32 v87, v87, v141
	v_lshlrev_b32_e32 v154, 16, v226
	v_and_b32_e32 v155, 0xffff0000, v226
	v_mul_f32_e32 v80, v80, v154
	v_mul_f32_e32 v81, v81, v155
	v_lshlrev_b32_e32 v158, 16, v227
	v_and_b32_e32 v141, 0xffff0000, v227
	v_mul_f32_e32 v82, v82, v158
	v_mul_f32_e32 v83, v83, v141
	v_cvt_pk_bf16_f32 v84, v84, v85
	v_cvt_pk_bf16_f32 v85, v86, v87
	v_cvt_pk_bf16_f32 v86, v80, v81
	v_cvt_pk_bf16_f32 v87, v82, v83
	global_store_dwordx4 v[148:149], v[84:87], off offset:256
	s_waitcnt vmcnt(15)
	v_lshlrev_b32_e32 v154, 16, v228
	v_and_b32_e32 v155, 0xffff0000, v228
	v_mul_f32_e32 v76, v76, v154
	v_mul_f32_e32 v77, v77, v155
	v_lshlrev_b32_e32 v158, 16, v229
	v_and_b32_e32 v141, 0xffff0000, v229
	v_mul_f32_e32 v78, v78, v158
	v_mul_f32_e32 v79, v79, v141
	v_lshlrev_b32_e32 v154, 16, v230
	v_and_b32_e32 v155, 0xffff0000, v230
	v_mul_f32_e32 v72, v72, v154
	v_mul_f32_e32 v73, v73, v155
	v_lshlrev_b32_e32 v158, 16, v231
	v_and_b32_e32 v141, 0xffff0000, v231
	v_mul_f32_e32 v74, v74, v158
	v_mul_f32_e32 v75, v75, v141
	v_add_u32_e32 v148, 0x30, v140
	v_ashrrev_i32_e32 v149, 31, v148
	v_lshlrev_b64 v[148:149], 11, v[148:149]
	v_lshl_add_u64 v[148:149], s[8:9], 0, v[148:149]
	v_lshl_add_u64 v[148:149], v[148:149], 0, v[138:139]
	v_cvt_pk_bf16_f32 v76, v76, v77
	v_cvt_pk_bf16_f32 v77, v78, v79
	v_cvt_pk_bf16_f32 v78, v72, v73
	v_cvt_pk_bf16_f32 v79, v74, v75
	global_store_dwordx4 v[148:149], v[76:79], off
	s_waitcnt vmcnt(15)
	v_lshlrev_b32_e32 v154, 16, v232
	v_and_b32_e32 v155, 0xffff0000, v232
	v_mul_f32_e32 v68, v68, v154
	v_mul_f32_e32 v69, v69, v155
	v_lshlrev_b32_e32 v158, 16, v233
	v_and_b32_e32 v141, 0xffff0000, v233
	v_mul_f32_e32 v70, v70, v158
	v_mul_f32_e32 v71, v71, v141
	v_lshlrev_b32_e32 v154, 16, v234
	v_and_b32_e32 v155, 0xffff0000, v234
	v_mul_f32_e32 v64, v64, v154
	v_mul_f32_e32 v65, v65, v155
	v_lshlrev_b32_e32 v158, 16, v235
	v_and_b32_e32 v141, 0xffff0000, v235
	v_mul_f32_e32 v66, v66, v158
	v_mul_f32_e32 v67, v67, v141
	v_cvt_pk_bf16_f32 v68, v68, v69
	v_cvt_pk_bf16_f32 v69, v70, v71
	v_cvt_pk_bf16_f32 v70, v64, v65
	v_cvt_pk_bf16_f32 v71, v66, v67
	global_store_dwordx4 v[148:149], v[68:71], off offset:256
	s_waitcnt vmcnt(15)
	v_lshlrev_b32_e32 v154, 16, v236
	v_and_b32_e32 v155, 0xffff0000, v236
	v_mul_f32_e32 v60, v60, v154
	v_mul_f32_e32 v61, v61, v155
	v_lshlrev_b32_e32 v158, 16, v237
	v_and_b32_e32 v141, 0xffff0000, v237
	v_mul_f32_e32 v62, v62, v158
	v_mul_f32_e32 v63, v63, v141
	v_lshlrev_b32_e32 v154, 16, v238
	v_and_b32_e32 v155, 0xffff0000, v238
	v_mul_f32_e32 v56, v56, v154
	v_mul_f32_e32 v57, v57, v155
	v_lshlrev_b32_e32 v158, 16, v239
	v_and_b32_e32 v141, 0xffff0000, v239
	v_mul_f32_e32 v58, v58, v158
	v_mul_f32_e32 v59, v59, v141
	v_add_u32_e32 v148, 0x80, v140
	v_ashrrev_i32_e32 v149, 31, v148
	v_lshlrev_b64 v[148:149], 11, v[148:149]
	v_lshl_add_u64 v[148:149], s[8:9], 0, v[148:149]
	v_lshl_add_u64 v[148:149], v[148:149], 0, v[138:139]
	v_cvt_pk_bf16_f32 v60, v60, v61
	v_cvt_pk_bf16_f32 v61, v62, v63
	v_cvt_pk_bf16_f32 v62, v56, v57
	v_cvt_pk_bf16_f32 v63, v58, v59
	global_store_dwordx4 v[148:149], v[60:63], off
	s_waitcnt vmcnt(15)
	v_lshlrev_b32_e32 v154, 16, v240
	v_and_b32_e32 v155, 0xffff0000, v240
	v_mul_f32_e32 v52, v52, v154
	v_mul_f32_e32 v53, v53, v155
	v_lshlrev_b32_e32 v158, 16, v241
	v_and_b32_e32 v141, 0xffff0000, v241
	v_mul_f32_e32 v54, v54, v158
	v_mul_f32_e32 v55, v55, v141
	v_lshlrev_b32_e32 v154, 16, v242
	v_and_b32_e32 v155, 0xffff0000, v242
	v_mul_f32_e32 v48, v48, v154
	v_mul_f32_e32 v49, v49, v155
	v_lshlrev_b32_e32 v158, 16, v243
	v_and_b32_e32 v141, 0xffff0000, v243
	v_mul_f32_e32 v50, v50, v158
	v_mul_f32_e32 v51, v51, v141
	v_cvt_pk_bf16_f32 v52, v52, v53
	v_cvt_pk_bf16_f32 v53, v54, v55
	v_cvt_pk_bf16_f32 v54, v48, v49
	v_cvt_pk_bf16_f32 v55, v50, v51
	global_store_dwordx4 v[148:149], v[52:55], off offset:256
	s_waitcnt vmcnt(15)
	v_lshlrev_b32_e32 v154, 16, v168
	v_and_b32_e32 v155, 0xffff0000, v168
	v_mul_f32_e32 v44, v44, v154
	v_mul_f32_e32 v45, v45, v155
	v_lshlrev_b32_e32 v158, 16, v169
	v_and_b32_e32 v141, 0xffff0000, v169
	v_mul_f32_e32 v46, v46, v158
	v_mul_f32_e32 v47, v47, v141
	v_lshlrev_b32_e32 v154, 16, v170
	v_and_b32_e32 v155, 0xffff0000, v170
	v_mul_f32_e32 v40, v40, v154
	v_mul_f32_e32 v41, v41, v155
	v_lshlrev_b32_e32 v158, 16, v171
	v_and_b32_e32 v141, 0xffff0000, v171
	v_mul_f32_e32 v42, v42, v158
	v_mul_f32_e32 v43, v43, v141
	v_add_u32_e32 v148, 0x90, v140
	v_ashrrev_i32_e32 v149, 31, v148
	v_lshlrev_b64 v[148:149], 11, v[148:149]
	v_lshl_add_u64 v[148:149], s[8:9], 0, v[148:149]
	v_lshl_add_u64 v[148:149], v[148:149], 0, v[138:139]
	v_cvt_pk_bf16_f32 v44, v44, v45
	v_cvt_pk_bf16_f32 v45, v46, v47
	v_cvt_pk_bf16_f32 v46, v40, v41
	v_cvt_pk_bf16_f32 v47, v42, v43
	global_store_dwordx4 v[148:149], v[44:47], off
	s_waitcnt vmcnt(15)
	v_lshlrev_b32_e32 v154, 16, v172
	v_and_b32_e32 v155, 0xffff0000, v172
	v_mul_f32_e32 v36, v36, v154
	v_mul_f32_e32 v37, v37, v155
	v_lshlrev_b32_e32 v158, 16, v173
	v_and_b32_e32 v141, 0xffff0000, v173
	v_mul_f32_e32 v38, v38, v158
	v_mul_f32_e32 v39, v39, v141
	v_lshlrev_b32_e32 v154, 16, v174
	v_and_b32_e32 v155, 0xffff0000, v174
	v_mul_f32_e32 v32, v32, v154
	v_mul_f32_e32 v33, v33, v155
	v_lshlrev_b32_e32 v158, 16, v175
	v_and_b32_e32 v141, 0xffff0000, v175
	v_mul_f32_e32 v34, v34, v158
	v_mul_f32_e32 v35, v35, v141
	v_cvt_pk_bf16_f32 v36, v36, v37
	v_cvt_pk_bf16_f32 v37, v38, v39
	v_cvt_pk_bf16_f32 v38, v32, v33
	v_cvt_pk_bf16_f32 v39, v34, v35
	global_store_dwordx4 v[148:149], v[36:39], off offset:256
	s_waitcnt vmcnt(15)
	v_lshlrev_b32_e32 v154, 16, v176
	v_and_b32_e32 v155, 0xffff0000, v176
	v_mul_f32_e32 v28, v28, v154
	v_mul_f32_e32 v29, v29, v155
	v_lshlrev_b32_e32 v158, 16, v177
	v_and_b32_e32 v141, 0xffff0000, v177
	v_mul_f32_e32 v30, v30, v158
	v_mul_f32_e32 v31, v31, v141
	v_lshlrev_b32_e32 v154, 16, v178
	v_and_b32_e32 v155, 0xffff0000, v178
	v_mul_f32_e32 v24, v24, v154
	v_mul_f32_e32 v25, v25, v155
	v_lshlrev_b32_e32 v158, 16, v179
	v_and_b32_e32 v141, 0xffff0000, v179
	v_mul_f32_e32 v26, v26, v158
	v_mul_f32_e32 v27, v27, v141
	v_add_u32_e32 v148, 0xa0, v140
	v_ashrrev_i32_e32 v149, 31, v148
	v_lshlrev_b64 v[148:149], 11, v[148:149]
	v_lshl_add_u64 v[148:149], s[8:9], 0, v[148:149]
	v_lshl_add_u64 v[148:149], v[148:149], 0, v[138:139]
	v_cvt_pk_bf16_f32 v28, v28, v29
	v_cvt_pk_bf16_f32 v29, v30, v31
	v_cvt_pk_bf16_f32 v30, v24, v25
	v_cvt_pk_bf16_f32 v31, v26, v27
	global_store_dwordx4 v[148:149], v[28:31], off
	s_waitcnt vmcnt(14)
	v_lshlrev_b32_e32 v154, 16, v204
	v_and_b32_e32 v155, 0xffff0000, v204
	v_mul_f32_e32 v20, v20, v154
	v_mul_f32_e32 v21, v21, v155
	v_lshlrev_b32_e32 v158, 16, v205
	v_and_b32_e32 v141, 0xffff0000, v205
	v_mul_f32_e32 v22, v22, v158
	v_mul_f32_e32 v23, v23, v141
	v_lshlrev_b32_e32 v154, 16, v206
	v_and_b32_e32 v155, 0xffff0000, v206
	v_mul_f32_e32 v16, v16, v154
	v_mul_f32_e32 v17, v17, v155
	v_lshlrev_b32_e32 v158, 16, v207
	v_and_b32_e32 v141, 0xffff0000, v207
	v_mul_f32_e32 v18, v18, v158
	v_mul_f32_e32 v19, v19, v141
	v_cvt_pk_bf16_f32 v20, v20, v21
	v_cvt_pk_bf16_f32 v21, v22, v23
	v_cvt_pk_bf16_f32 v22, v16, v17
	v_cvt_pk_bf16_f32 v23, v18, v19
	global_store_dwordx4 v[148:149], v[20:23], off offset:256
	s_waitcnt vmcnt(13)
	v_lshlrev_b32_e32 v154, 16, v208
	v_and_b32_e32 v155, 0xffff0000, v208
	v_mul_f32_e32 v12, v12, v154
	v_mul_f32_e32 v13, v13, v155
	v_lshlrev_b32_e32 v158, 16, v209
	v_and_b32_e32 v141, 0xffff0000, v209
	v_mul_f32_e32 v14, v14, v158
	v_mul_f32_e32 v15, v15, v141
	v_lshlrev_b32_e32 v154, 16, v210
	v_and_b32_e32 v155, 0xffff0000, v210
	v_mul_f32_e32 v8, v8, v154
	v_mul_f32_e32 v9, v9, v155
	v_lshlrev_b32_e32 v158, 16, v211
	v_and_b32_e32 v141, 0xffff0000, v211
	v_mul_f32_e32 v10, v10, v158
	v_mul_f32_e32 v11, v11, v141
	v_add_u32_e32 v148, 0xb0, v140
	v_ashrrev_i32_e32 v149, 31, v148
	v_lshlrev_b64 v[148:149], 11, v[148:149]
	v_lshl_add_u64 v[148:149], s[8:9], 0, v[148:149]
	v_lshl_add_u64 v[148:149], v[148:149], 0, v[138:139]
	v_cvt_pk_bf16_f32 v12, v12, v13
	v_cvt_pk_bf16_f32 v13, v14, v15
	v_cvt_pk_bf16_f32 v14, v8, v9
	v_cvt_pk_bf16_f32 v15, v10, v11
	global_store_dwordx4 v[148:149], v[12:15], off
	s_waitcnt vmcnt(12)
	v_lshlrev_b32_e32 v154, 16, v212
	v_and_b32_e32 v155, 0xffff0000, v212
	v_mul_f32_e32 v4, v4, v154
	v_mul_f32_e32 v5, v5, v155
	v_lshlrev_b32_e32 v158, 16, v213
	v_and_b32_e32 v141, 0xffff0000, v213
	v_mul_f32_e32 v6, v6, v158
	v_mul_f32_e32 v7, v7, v141
	v_lshlrev_b32_e32 v154, 16, v214
	v_and_b32_e32 v155, 0xffff0000, v214
	v_mul_f32_e32 v0, v0, v154
	v_mul_f32_e32 v1, v1, v155
	v_lshlrev_b32_e32 v158, 16, v215
	v_and_b32_e32 v141, 0xffff0000, v215
	v_mul_f32_e32 v2, v2, v158
	v_mul_f32_e32 v3, v3, v141
	v_cvt_pk_bf16_f32 v4, v4, v5
	v_cvt_pk_bf16_f32 v5, v6, v7
	v_cvt_pk_bf16_f32 v6, v0, v1
	v_cvt_pk_bf16_f32 v7, v2, v3
	global_store_dwordx4 v[148:149], v[4:7], off offset:256
	s_mov_b64 s[8:9], -1
	s_andn2_b64 vcc, exec, s[38:39]
	s_cbranch_vccnz .LBB0_120
	s_andn2_b64 vcc, exec, s[0:1]
	s_cbranch_vccnz .LBB0_119
	s_barrier
	s_branch .LBB0_119
